# attention K-loop: next K/V tile staged into LDS before the row-sum instead of at the iteration end (ring slots are free all iteration)
# baseline (speedup 1.0000x reference)
.LBB0_229:
	s_andn2_b64 vcc, exec, s[62:63]
	s_cbranch_vccnz .Learly_store_skip_233
	s_mul_hi_u32 s17, s16, 0xaaaaaaab
	s_lshr_b32 s17, s17, 1
	s_bitcmp1_b32 s16, 0
	s_cselect_b32 s20, 0x4800, 0
	s_mul_i32 s17, s17, 0xffff2800
	v_add_u32_e32 v102, s20, v161
	s_waitcnt vmcnt(3)
	ds_write_b128 v102, v[128:131]
	s_waitcnt vmcnt(2)
	ds_write_b128 v102, v[132:135] offset:9216
	v_add_u32_e32 v102, s17, v225
	s_waitcnt vmcnt(1)
	ds_write_b128 v102, v[136:139] offset:36864
	s_waitcnt vmcnt(0)
	ds_write_b128 v102, v[140:143] offset:46080
.Learly_store_skip_233:
	v_add_f32_e32 v173, v173, v229
	v_add_f32_e32 v230, v230, v231
	v_add_f32_e32 v232, v232, v233
	v_add_f32_e32 v234, v234, v235
	v_add_f32_e32 v236, v236, v237
	v_add_f32_e32 v238, v238, v239
	v_add_f32_e32 v240, v240, v241
	v_add_f32_e32 v242, v242, v243
	v_add_f32_e32 v1, v1, v3
	v_add_f32_e32 v4, v4, v5
	v_add_f32_e32 v6, v6, v7
	v_add_f32_e32 v8, v8, v9
	v_add_f32_e32 v10, v10, v11
	v_add_f32_e32 v12, v12, v13
	v_add_f32_e32 v14, v14, v15
	v_add_f32_e32 v96, v96, v97
	v_add_f32_e32 v173, v173, v230
	v_add_f32_e32 v232, v232, v234
	v_add_f32_e32 v236, v236, v238
	v_add_f32_e32 v240, v240, v242
	v_add_f32_e32 v1, v1, v4
	v_add_f32_e32 v6, v6, v8
	v_add_f32_e32 v10, v10, v12
	v_add_f32_e32 v14, v14, v96
	v_add_f32_e32 v173, v173, v232
	v_add_f32_e32 v236, v236, v240
	v_add_f32_e32 v1, v1, v6
	v_add_f32_e32 v10, v10, v14
	v_add_f32_e32 v173, v173, v236
	v_add_f32_e32 v1, v1, v10
	v_add_f32_e32 v1, v1, v173
	v_add_f32_e32 v2, v2, v1
	s_mov_b64 s[64:65], 0
	s_branch .LBB0_214

.LBB0_1295:
	s_andn2_b64 vcc, exec, s[62:63]
	s_cbranch_vccnz .Learly_store_skip_1299
	s_mul_hi_u32 s17, s16, 0xaaaaaaab
	s_lshr_b32 s17, s17, 1
	s_bitcmp1_b32 s16, 0
	s_cselect_b32 s20, 0x4800, 0
	s_mul_i32 s17, s17, 0xffff2800
	v_add_u32_e32 v102, s20, v161
	s_waitcnt vmcnt(3)
	ds_write_b128 v102, v[128:131]
	s_waitcnt vmcnt(2)
	ds_write_b128 v102, v[132:135] offset:9216
	v_add_u32_e32 v102, s17, v227
	s_waitcnt vmcnt(1)
	ds_write_b128 v102, v[136:139] offset:36864
	s_waitcnt vmcnt(0)
	ds_write_b128 v102, v[140:143] offset:46080
.Learly_store_skip_1299:
	v_add_f32_e32 v173, v173, v231
	v_add_f32_e32 v232, v232, v233
	v_add_f32_e32 v234, v234, v235
	v_add_f32_e32 v236, v236, v237
	v_add_f32_e32 v238, v238, v239
	v_add_f32_e32 v241, v241, v242
	v_add_f32_e32 v243, v243, v244
	v_add_f32_e32 v245, v245, v246
	v_add_f32_e32 v1, v1, v3
	v_add_f32_e32 v4, v4, v5
	v_add_f32_e32 v6, v6, v7
	v_add_f32_e32 v8, v8, v9
	v_add_f32_e32 v10, v10, v11
	v_add_f32_e32 v12, v12, v13
	v_add_f32_e32 v14, v14, v15
	v_add_f32_e32 v96, v96, v97
	v_add_f32_e32 v173, v173, v232
	v_add_f32_e32 v234, v234, v236
	v_add_f32_e32 v238, v238, v241
	v_add_f32_e32 v243, v243, v245
	v_add_f32_e32 v1, v1, v4
	v_add_f32_e32 v6, v6, v8
	v_add_f32_e32 v10, v10, v12
	v_add_f32_e32 v14, v14, v96
	v_add_f32_e32 v173, v173, v234
	v_add_f32_e32 v238, v238, v243
	v_add_f32_e32 v1, v1, v6
	v_add_f32_e32 v10, v10, v14
	v_add_f32_e32 v173, v173, v238
	v_add_f32_e32 v1, v1, v10
	v_add_f32_e32 v1, v1, v173
	v_add_f32_e32 v2, v2, v1
	s_mov_b64 s[64:65], 0
	s_branch .LBB0_1280
